# GEMM main loop: redundant lgkmcnt(0) right after each segment barrier removed (the wait before the barrier already drains LDS reads)
# baseline (speedup 1.0000x reference)
; #define PG8_STAGE(bufoff, gbase, voff) do { _Pragma("unroll") for (int _i = 0; _i < 2; ++_i) \
;         __builtin_amdgcn_global_load_lds((const unsigned*)((const char*)(gbase) + (voff)[_i]), (LAS unsigned*)(lds + (bufoff) + ldsw + _i * 8192), 16, 0, 0); } while (0)
; #define PG8_LDA(dst, b, h) do { _Pragma("unroll") for (int m = 0; m < 4; ++m) _Pragma("unroll") for (int k = 0; k < 2; ++k) dst[m][k] = *(const LAS bf16x8*)(lds + PG8_SA(b, h) + aoff + m * 2048 + k * 1024); } while (0)
; #define PG8_LDB(dst, b, h) do { _Pragma("unroll") for (int n = 0; n < 2; ++n) _Pragma("unroll") for (int k = 0; k < 2; ++k) dst[n][k] = *(const LAS bf16x8*)(lds + PG8_SB(b, h) + boff + n * 2048 + k * 1024); } while (0)
; #define PG8_MMA(ai, bj, At, Bt) do { __builtin_amdgcn_s_setprio(1); _Pragma("unroll") for (int m = 0; m < 4; ++m) _Pragma("unroll") for (int n = 0; n < 2; ++n) _Pragma("unroll") for (int k = 0; k < 2; ++k) \
;         acc[ai][bj][m][n] = __builtin_amdgcn_mfma_f32_16x16x32_bf16(Bt[n][k], At[m][k], acc[ai][bj][m][n], 0, 0, 0); __builtin_amdgcn_s_setprio(0); } while (0)
; #define PG8_WAIT_V(n) asm volatile("s_waitcnt vmcnt(" #n ")" ::: "memory")
; #define PG8_WAIT_L(n) asm volatile("s_waitcnt lgkmcnt(" #n ")" ::: "memory")
; #define PG8_BAR __builtin_amdgcn_s_barrier()
; #define PG8_SCHED __builtin_amdgcn_sched_barrier(0)
; __device__ __forceinline__ void gemm_phase(LAS unsigned char* lds, const GemmD g, const Sched& S, const Epi& E) {
;     ...
;         for (int t = 0; t < nt; t += 2) {
;             const bool last = (t == nt - 2);
;             const char* a1 = cA + (size_t)(t + 1) * kstep;
;             const char* a2 = last ? nA : cA + (size_t)(t + 2) * kstep; const char* b2 = last ? nB : cB + (size_t)(t + 2) * kstep;
;             const char* a3 = a2 + kstep; const char* b3 = b2 + kstep;
;             PG8_LDB(B0, 0, 0); PG8_LDB(B1, 0, 1); PG8_SCHED; PG8_LDA(At, 0, 0); PG8_STAGE(PG8_SA(1, 1), a1 + hstepA, voffA);
;             PG8_WAIT_V(8); PG8_WAIT_L(0); PG8_BAR; PG8_MMA(0, 0, At, B0); PG8_MMA(0, 1, At, B1); PG8_BAR; PG8_SCHED;
;             PG8_LDA(At, 0, 1); PG8_STAGE(PG8_SB(0, 0), b2, voffB); PG8_STAGE(PG8_SB(0, 1), b2 + hstepB, voffB); PG8_STAGE(PG8_SA(0, 0), a2, voffA);
;             PG8_WAIT_V(8); PG8_WAIT_L(0); PG8_BAR; PG8_MMA(1, 0, At, B0); PG8_MMA(1, 1, At, B1); PG8_BAR; PG8_SCHED;
.Lprio_done:
	v_add_u32_e32 v240, 0x10000, v160
	v_add_u32_e32 v241, 0x14000, v160
	v_add_u32_e32 v242, 0x18000, v160
	v_add_u32_e32 v243, 0x1c000, v160
	s_add_i32 s92, s26, 2
	s_add_u32 s93, s8, 0x80
	s_addc_u32 s27, s9, 0
	s_add_i32 s22, 0, 0x10000
	s_cmp_eq_u32 s11, s26
	s_cselect_b32 s27, s1, s27
	s_cselect_b32 s26, s0, s93
	s_cselect_b32 vcc_hi, s17, s35
	s_cselect_b32 vcc_lo, s16, s34
	s_add_i32 s23, 0, 0x14000
	ds_read_b128 v[130:133], v240
	ds_read_b128 v[146:149], v240 offset:1024
	ds_read_b128 v[150:153], v240 offset:2048
	ds_read_b128 v[154:157], v240 offset:3072
	ds_read_b128 v[162:165], v241
	ds_read_b128 v[166:169], v241 offset:1024
	ds_read_b128 v[170:173], v241 offset:2048
	ds_read_b128 v[174:177], v241 offset:3072
	s_add_i32 m0, s31, 0xc000
	ds_read_b128 v[182:185], v161
	ds_read_b128 v[186:189], v161 offset:1024
	ds_read_b128 v[190:193], v161 offset:2048
	ds_read_b128 v[216:219], v161 offset:3072
	ds_read_b128 v[220:223], v161 offset:4096
	ds_read_b128 v[224:227], v161 offset:5120
	ds_read_b128 v[228:231], v161 offset:6144
	ds_read_b128 v[236:239], v161 offset:7168
	global_load_lds_dwordx4 v142, s[8:9]
	s_add_i32 m0, s31, 0xe000
	s_nop 0
	global_load_lds_dwordx4 v144, s[8:9]
	s_waitcnt vmcnt(8)
	s_waitcnt lgkmcnt(0)
	s_barrier
	v_mfma_f32_16x16x32_bf16 v[126:129], v[130:133], v[182:185], 0
	v_mfma_f32_16x16x32_bf16 v[122:125], v[150:153], v[182:185], 0
	v_mfma_f32_16x16x32_bf16 v[110:113], v[130:133], v[190:193], 0
	v_mfma_f32_16x16x32_bf16 v[106:109], v[150:153], v[190:193], 0
	v_mfma_f32_16x16x32_bf16 v[94:97], v[130:133], v[220:223], 0
	v_mfma_f32_16x16x32_bf16 v[90:93], v[150:153], v[220:223], 0
	v_mfma_f32_16x16x32_bf16 v[78:81], v[130:133], v[228:231], 0
	v_mfma_f32_16x16x32_bf16 v[74:77], v[150:153], v[228:231], 0
	v_mfma_f32_16x16x32_bf16 v[126:129], v[146:149], v[186:189], v[126:129]
	v_mfma_f32_16x16x32_bf16 v[122:125], v[154:157], v[186:189], v[122:125]
	v_mfma_f32_16x16x32_bf16 v[110:113], v[146:149], v[216:219], v[110:113]
	v_mfma_f32_16x16x32_bf16 v[106:109], v[154:157], v[216:219], v[106:109]
	v_mfma_f32_16x16x32_bf16 v[94:97], v[146:149], v[224:227], v[94:97]
	v_mfma_f32_16x16x32_bf16 v[90:93], v[154:157], v[224:227], v[90:93]
	v_mfma_f32_16x16x32_bf16 v[78:81], v[146:149], v[236:239], v[78:81]
	v_mfma_f32_16x16x32_bf16 v[74:77], v[154:157], v[236:239], v[74:77]
	v_mfma_f32_16x16x32_bf16 v[118:121], v[162:165], v[182:185], 0
	v_mfma_f32_16x16x32_bf16 v[114:117], v[170:173], v[182:185], 0
	v_mfma_f32_16x16x32_bf16 v[102:105], v[162:165], v[190:193], 0
	v_mfma_f32_16x16x32_bf16 v[98:101], v[170:173], v[190:193], 0
	v_mfma_f32_16x16x32_bf16 v[86:89], v[162:165], v[220:223], 0
	v_mfma_f32_16x16x32_bf16 v[82:85], v[170:173], v[220:223], 0
	v_mfma_f32_16x16x32_bf16 v[70:73], v[162:165], v[228:231], 0
	v_mfma_f32_16x16x32_bf16 v[66:69], v[170:173], v[228:231], 0
	v_mfma_f32_16x16x32_bf16 v[118:121], v[166:169], v[186:189], v[118:121]
	v_mfma_f32_16x16x32_bf16 v[114:117], v[174:177], v[186:189], v[114:117]
	v_mfma_f32_16x16x32_bf16 v[102:105], v[166:169], v[216:219], v[102:105]
	v_mfma_f32_16x16x32_bf16 v[98:101], v[174:177], v[216:219], v[98:101]
	v_mfma_f32_16x16x32_bf16 v[86:89], v[166:169], v[224:227], v[86:89]
	v_mfma_f32_16x16x32_bf16 v[82:85], v[174:177], v[224:227], v[82:85]
	v_mfma_f32_16x16x32_bf16 v[70:73], v[166:169], v[236:239], v[70:73]
	v_mfma_f32_16x16x32_bf16 v[66:69], v[174:177], v[236:239], v[66:69]
	s_barrier
	s_add_i32 s22, s22, s30
	s_mov_b32 m0, s22
	ds_read_b128 v[182:185], v161 offset:16384
	ds_read_b128 v[186:189], v161 offset:17408
	ds_read_b128 v[190:193], v161 offset:18432
	ds_read_b128 v[216:219], v161 offset:19456
	ds_read_b128 v[220:223], v161 offset:20480
	ds_read_b128 v[224:227], v161 offset:21504
	ds_read_b128 v[228:231], v161 offset:22528
	ds_read_b128 v[236:239], v161 offset:23552
	global_load_lds_dwordx4 v136, vcc
	s_add_i32 m0, s22, 0x2000
	s_add_i32 s22, s23, s30
	global_load_lds_dwordx4 v140, vcc
	s_mov_b32 m0, s22
	s_nop 0
	global_load_lds_dwordx4 v253, vcc
	s_add_i32 m0, s22, 0x2000
	s_nop 0
	global_load_lds_dwordx4 v254, vcc
	s_mov_b32 m0, s31
	s_nop 0
	global_load_lds_dwordx4 v134, s[26:27]
	s_mov_b32 m0, s14
	s_nop 0
	global_load_lds_dwordx4 v138, s[26:27]
	s_waitcnt vmcnt(8)
	s_waitcnt lgkmcnt(0)
	s_barrier
	v_mfma_f32_16x16x32_bf16 v[62:65], v[130:133], v[182:185], 0
	v_mfma_f32_16x16x32_bf16 v[58:61], v[150:153], v[182:185], 0
	v_mfma_f32_16x16x32_bf16 v[46:49], v[130:133], v[190:193], 0
	v_mfma_f32_16x16x32_bf16 v[42:45], v[150:153], v[190:193], 0
	v_mfma_f32_16x16x32_bf16 v[30:33], v[130:133], v[220:223], 0
	v_mfma_f32_16x16x32_bf16 v[26:29], v[150:153], v[220:223], 0
	v_mfma_f32_16x16x32_bf16 v[14:17], v[130:133], v[228:231], 0
	v_mfma_f32_16x16x32_bf16 v[10:13], v[150:153], v[228:231], 0
	v_mfma_f32_16x16x32_bf16 v[62:65], v[146:149], v[186:189], v[62:65]
	v_mfma_f32_16x16x32_bf16 v[58:61], v[154:157], v[186:189], v[58:61]
	v_mfma_f32_16x16x32_bf16 v[46:49], v[146:149], v[216:219], v[46:49]
	v_mfma_f32_16x16x32_bf16 v[42:45], v[154:157], v[216:219], v[42:45]
	v_mfma_f32_16x16x32_bf16 v[30:33], v[146:149], v[224:227], v[30:33]
	v_mfma_f32_16x16x32_bf16 v[26:29], v[154:157], v[224:227], v[26:29]
	v_mfma_f32_16x16x32_bf16 v[14:17], v[146:149], v[236:239], v[14:17]
	v_mfma_f32_16x16x32_bf16 v[10:13], v[154:157], v[236:239], v[10:13]
	v_mfma_f32_16x16x32_bf16 v[54:57], v[162:165], v[182:185], 0
	v_mfma_f32_16x16x32_bf16 v[50:53], v[170:173], v[182:185], 0
	v_mfma_f32_16x16x32_bf16 v[38:41], v[162:165], v[190:193], 0
	v_mfma_f32_16x16x32_bf16 v[34:37], v[170:173], v[190:193], 0
	v_mfma_f32_16x16x32_bf16 v[22:25], v[162:165], v[220:223], 0
	v_mfma_f32_16x16x32_bf16 v[18:21], v[170:173], v[220:223], 0
	v_mfma_f32_16x16x32_bf16 v[6:9], v[162:165], v[228:231], 0
	v_mfma_f32_16x16x32_bf16 v[2:5], v[170:173], v[228:231], 0
	v_mfma_f32_16x16x32_bf16 v[54:57], v[166:169], v[186:189], v[54:57]
	v_mfma_f32_16x16x32_bf16 v[50:53], v[174:177], v[186:189], v[50:53]
	v_mfma_f32_16x16x32_bf16 v[38:41], v[166:169], v[216:219], v[38:41]
	v_mfma_f32_16x16x32_bf16 v[34:37], v[174:177], v[216:219], v[34:37]
	v_mfma_f32_16x16x32_bf16 v[22:25], v[166:169], v[224:227], v[22:25]
	v_mfma_f32_16x16x32_bf16 v[18:21], v[174:177], v[224:227], v[18:21]
	v_mfma_f32_16x16x32_bf16 v[6:9], v[166:169], v[236:239], v[6:9]
	v_mfma_f32_16x16x32_bf16 v[2:5], v[174:177], v[236:239], v[2:5]
	s_barrier
; #define PG8_STAGE(bufoff, gbase, voff) do { _Pragma("unroll") for (int _i = 0; _i < 2; ++_i) \
;         __builtin_amdgcn_global_load_lds((const unsigned*)((const char*)(gbase) + (voff)[_i]), (LAS unsigned*)(lds + (bufoff) + ldsw + _i * 8192), 16, 0, 0); } while (0)
; #define PG8_LDA(dst, b, h) do { _Pragma("unroll") for (int m = 0; m < 4; ++m) _Pragma("unroll") for (int k = 0; k < 2; ++k) dst[m][k] = *(const LAS bf16x8*)(lds + PG8_SA(b, h) + aoff + m * 2048 + k * 1024); } while (0)
; #define PG8_LDB(dst, b, h) do { _Pragma("unroll") for (int n = 0; n < 2; ++n) _Pragma("unroll") for (int k = 0; k < 2; ++k) dst[n][k] = *(const LAS bf16x8*)(lds + PG8_SB(b, h) + boff + n * 2048 + k * 1024); } while (0)
; #define PG8_MMA(ai, bj, At, Bt) do { __builtin_amdgcn_s_setprio(1); _Pragma("unroll") for (int m = 0; m < 4; ++m) _Pragma("unroll") for (int n = 0; n < 2; ++n) _Pragma("unroll") for (int k = 0; k < 2; ++k) \
;         acc[ai][bj][m][n] = __builtin_amdgcn_mfma_f32_16x16x32_bf16(Bt[n][k], At[m][k], acc[ai][bj][m][n], 0, 0, 0); __builtin_amdgcn_s_setprio(0); } while (0)
; #define PG8_WAIT_V(n) asm volatile("s_waitcnt vmcnt(" #n ")" ::: "memory")
; #define PG8_WAIT_L(n) asm volatile("s_waitcnt lgkmcnt(" #n ")" ::: "memory")
; #define PG8_BAR __builtin_amdgcn_s_barrier()
; #define PG8_SCHED __builtin_amdgcn_sched_barrier(0)
; __device__ __forceinline__ void gemm_phase(LAS unsigned char* lds, const GemmD g, const Sched& S, const Epi& E) {
;     ...
;             PG8_LDB(B0, 1, 0); PG8_LDB(B1, 1, 1); PG8_SCHED; PG8_LDA(At, 1, 0); PG8_STAGE(PG8_SA(0, 1), a2 + hstepA, voffA);
;             PG8_WAIT_V(8); PG8_WAIT_L(0); PG8_BAR; PG8_MMA(0, 0, At, B0); PG8_MMA(0, 1, At, B1); PG8_BAR; PG8_SCHED;
;             PG8_LDA(At, 1, 1); PG8_STAGE(PG8_SB(1, 0), b3, voffB); PG8_STAGE(PG8_SB(1, 1), b3 + hstepB, voffB); PG8_STAGE(PG8_SA(1, 0), a3, voffA);
;             PG8_WAIT_V(8); PG8_WAIT_L(0); PG8_BAR; PG8_MMA(1, 0, At, B0); PG8_MMA(1, 1, At, B1); PG8_BAR; PG8_SCHED;
;         }
	s_add_i32 s22, 0, 0x18000
	s_add_i32 s23, 0, 0x1c000
	ds_read_b128 v[130:133], v242
	ds_read_b128 v[146:149], v242 offset:1024
	ds_read_b128 v[150:153], v242 offset:2048
	ds_read_b128 v[154:157], v242 offset:3072
	ds_read_b128 v[162:165], v243
	ds_read_b128 v[166:169], v243 offset:1024
	ds_read_b128 v[170:173], v243 offset:2048
	ds_read_b128 v[174:177], v243 offset:3072
	s_mov_b32 m0, s15
	ds_read_b128 v[182:185], v161 offset:32768
	ds_read_b128 v[186:189], v161 offset:33792
	ds_read_b128 v[190:193], v161 offset:34816
	ds_read_b128 v[216:219], v161 offset:35840
	ds_read_b128 v[220:223], v161 offset:36864
	ds_read_b128 v[224:227], v161 offset:37888
	ds_read_b128 v[228:231], v161 offset:38912
	ds_read_b128 v[236:239], v161 offset:39936
	global_load_lds_dwordx4 v142, s[26:27]
	s_mov_b32 m0, s10
	s_nop 0
	global_load_lds_dwordx4 v144, s[26:27]
	s_waitcnt vmcnt(8)
	s_waitcnt lgkmcnt(0)
	s_barrier
	v_mfma_f32_16x16x32_bf16 v[126:129], v[130:133], v[182:185], v[126:129]
	v_mfma_f32_16x16x32_bf16 v[122:125], v[150:153], v[182:185], v[122:125]
	v_mfma_f32_16x16x32_bf16 v[110:113], v[130:133], v[190:193], v[110:113]
	v_mfma_f32_16x16x32_bf16 v[106:109], v[150:153], v[190:193], v[106:109]
	v_mfma_f32_16x16x32_bf16 v[94:97], v[130:133], v[220:223], v[94:97]
	v_mfma_f32_16x16x32_bf16 v[90:93], v[150:153], v[220:223], v[90:93]
	v_mfma_f32_16x16x32_bf16 v[78:81], v[130:133], v[228:231], v[78:81]
	v_mfma_f32_16x16x32_bf16 v[74:77], v[150:153], v[228:231], v[74:77]
	v_mfma_f32_16x16x32_bf16 v[126:129], v[146:149], v[186:189], v[126:129]
	v_mfma_f32_16x16x32_bf16 v[122:125], v[154:157], v[186:189], v[122:125]
	v_mfma_f32_16x16x32_bf16 v[110:113], v[146:149], v[216:219], v[110:113]
	v_mfma_f32_16x16x32_bf16 v[106:109], v[154:157], v[216:219], v[106:109]
	v_mfma_f32_16x16x32_bf16 v[94:97], v[146:149], v[224:227], v[94:97]
	v_mfma_f32_16x16x32_bf16 v[90:93], v[154:157], v[224:227], v[90:93]
	v_mfma_f32_16x16x32_bf16 v[78:81], v[146:149], v[236:239], v[78:81]
	v_mfma_f32_16x16x32_bf16 v[74:77], v[154:157], v[236:239], v[74:77]
	v_mfma_f32_16x16x32_bf16 v[118:121], v[162:165], v[182:185], v[118:121]
	v_mfma_f32_16x16x32_bf16 v[114:117], v[170:173], v[182:185], v[114:117]
	v_mfma_f32_16x16x32_bf16 v[102:105], v[162:165], v[190:193], v[102:105]
	v_mfma_f32_16x16x32_bf16 v[98:101], v[170:173], v[190:193], v[98:101]
	v_mfma_f32_16x16x32_bf16 v[86:89], v[162:165], v[220:223], v[86:89]
	v_mfma_f32_16x16x32_bf16 v[82:85], v[170:173], v[220:223], v[82:85]
	v_mfma_f32_16x16x32_bf16 v[70:73], v[162:165], v[228:231], v[70:73]
	v_mfma_f32_16x16x32_bf16 v[66:69], v[170:173], v[228:231], v[66:69]
	v_mfma_f32_16x16x32_bf16 v[118:121], v[166:169], v[186:189], v[118:121]
	v_mfma_f32_16x16x32_bf16 v[114:117], v[174:177], v[186:189], v[114:117]
	v_mfma_f32_16x16x32_bf16 v[102:105], v[166:169], v[216:219], v[102:105]
	v_mfma_f32_16x16x32_bf16 v[98:101], v[174:177], v[216:219], v[98:101]
	v_mfma_f32_16x16x32_bf16 v[86:89], v[166:169], v[224:227], v[86:89]
	v_mfma_f32_16x16x32_bf16 v[82:85], v[174:177], v[224:227], v[82:85]
	v_mfma_f32_16x16x32_bf16 v[70:73], v[166:169], v[236:239], v[70:73]
	v_mfma_f32_16x16x32_bf16 v[66:69], v[174:177], v[236:239], v[66:69]
	s_barrier
	s_add_i32 s22, s22, s30
	s_add_u32 vcc_lo, vcc_lo, s84
	s_addc_u32 vcc_hi, vcc_hi, s85
	s_add_u32 s26, s26, s84
	s_addc_u32 s27, s27, s85
	s_mov_b32 m0, s22
	ds_read_b128 v[182:185], v161 offset:49152
	ds_read_b128 v[186:189], v161 offset:50176
	ds_read_b128 v[190:193], v161 offset:51200
	ds_read_b128 v[216:219], v161 offset:52224
	ds_read_b128 v[220:223], v161 offset:53248
	ds_read_b128 v[224:227], v161 offset:54272
	ds_read_b128 v[228:231], v161 offset:55296
	ds_read_b128 v[236:239], v161 offset:56320
	global_load_lds_dwordx4 v136, vcc
	s_add_i32 m0, s22, 0x2000
	s_add_i32 s22, s23, s30
	global_load_lds_dwordx4 v140, vcc
	s_mov_b32 m0, s22
	s_nop 0
	global_load_lds_dwordx4 v253, vcc
	s_add_i32 m0, s22, 0x2000
	s_nop 0
	global_load_lds_dwordx4 v254, vcc
	s_mov_b32 m0, s18
	s_nop 0
	global_load_lds_dwordx4 v134, s[26:27]
	s_mov_b32 m0, s19
	s_nop 0
	global_load_lds_dwordx4 v138, s[26:27]
	s_waitcnt vmcnt(8)
	s_waitcnt lgkmcnt(0)
	s_barrier
	v_mfma_f32_16x16x32_bf16 v[62:65], v[130:133], v[182:185], v[62:65]
	v_mfma_f32_16x16x32_bf16 v[58:61], v[150:153], v[182:185], v[58:61]
	v_mfma_f32_16x16x32_bf16 v[46:49], v[130:133], v[190:193], v[46:49]
	v_mfma_f32_16x16x32_bf16 v[42:45], v[150:153], v[190:193], v[42:45]
	v_mfma_f32_16x16x32_bf16 v[30:33], v[130:133], v[220:223], v[30:33]
	v_mfma_f32_16x16x32_bf16 v[26:29], v[150:153], v[220:223], v[26:29]
	v_mfma_f32_16x16x32_bf16 v[14:17], v[130:133], v[228:231], v[14:17]
	v_mfma_f32_16x16x32_bf16 v[10:13], v[150:153], v[228:231], v[10:13]
	v_mfma_f32_16x16x32_bf16 v[62:65], v[146:149], v[186:189], v[62:65]
	v_mfma_f32_16x16x32_bf16 v[58:61], v[154:157], v[186:189], v[58:61]
	v_mfma_f32_16x16x32_bf16 v[46:49], v[146:149], v[216:219], v[46:49]
	v_mfma_f32_16x16x32_bf16 v[42:45], v[154:157], v[216:219], v[42:45]
	v_mfma_f32_16x16x32_bf16 v[30:33], v[146:149], v[224:227], v[30:33]
	v_mfma_f32_16x16x32_bf16 v[26:29], v[154:157], v[224:227], v[26:29]
	v_mfma_f32_16x16x32_bf16 v[14:17], v[146:149], v[236:239], v[14:17]
	v_mfma_f32_16x16x32_bf16 v[10:13], v[154:157], v[236:239], v[10:13]
	v_mfma_f32_16x16x32_bf16 v[54:57], v[162:165], v[182:185], v[54:57]
	v_mfma_f32_16x16x32_bf16 v[50:53], v[170:173], v[182:185], v[50:53]
	v_mfma_f32_16x16x32_bf16 v[38:41], v[162:165], v[190:193], v[38:41]
	v_mfma_f32_16x16x32_bf16 v[34:37], v[170:173], v[190:193], v[34:37]
	v_mfma_f32_16x16x32_bf16 v[22:25], v[162:165], v[220:223], v[22:25]
	v_mfma_f32_16x16x32_bf16 v[18:21], v[170:173], v[220:223], v[18:21]
	v_mfma_f32_16x16x32_bf16 v[6:9], v[162:165], v[228:231], v[6:9]
	v_mfma_f32_16x16x32_bf16 v[2:5], v[170:173], v[228:231], v[2:5]
	v_mfma_f32_16x16x32_bf16 v[54:57], v[166:169], v[186:189], v[54:57]
	v_mfma_f32_16x16x32_bf16 v[50:53], v[174:177], v[186:189], v[50:53]
	v_mfma_f32_16x16x32_bf16 v[38:41], v[166:169], v[216:219], v[38:41]
	v_mfma_f32_16x16x32_bf16 v[34:37], v[174:177], v[216:219], v[34:37]
	v_mfma_f32_16x16x32_bf16 v[22:25], v[166:169], v[224:227], v[22:25]
	v_mfma_f32_16x16x32_bf16 v[18:21], v[174:177], v[224:227], v[18:21]
	v_mfma_f32_16x16x32_bf16 v[6:9], v[166:169], v[236:239], v[6:9]
	v_mfma_f32_16x16x32_bf16 v[2:5], v[174:177], v[236:239], v[2:5]
	s_barrier
	s_add_u32 s8, s8, 0x100
	s_addc_u32 s9, s9, 0
	s_add_u32 s34, s34, 0x100
	s_addc_u32 s35, s35, 0
	s_cmp_ge_u32 s92, s12
	s_mov_b32 s26, s92
	s_cbranch_scc0 .LBB0_215
	s_branch .Lgemm_after
; #define PG8_STAGE(bufoff, gbase, voff) do { _Pragma("unroll") for (int _i = 0; _i < 2; ++_i) \
;         __builtin_amdgcn_global_load_lds((const unsigned*)((const char*)(gbase) + (voff)[_i]), (LAS unsigned*)(lds + (bufoff) + ldsw + _i * 8192), 16, 0, 0); } while (0)
; #define PG8_LDA(dst, b, h) do { _Pragma("unroll") for (int m = 0; m < 4; ++m) _Pragma("unroll") for (int k = 0; k < 2; ++k) dst[m][k] = *(const LAS bf16x8*)(lds + PG8_SA(b, h) + aoff + m * 2048 + k * 1024); } while (0)
; #define PG8_LDB(dst, b, h) do { _Pragma("unroll") for (int n = 0; n < 2; ++n) _Pragma("unroll") for (int k = 0; k < 2; ++k) dst[n][k] = *(const LAS bf16x8*)(lds + PG8_SB(b, h) + boff + n * 2048 + k * 1024); } while (0)
; #define PG8_MMA(ai, bj, At, Bt) do { __builtin_amdgcn_s_setprio(1); _Pragma("unroll") for (int m = 0; m < 4; ++m) _Pragma("unroll") for (int n = 0; n < 2; ++n) _Pragma("unroll") for (int k = 0; k < 2; ++k) \
;         acc[ai][bj][m][n] = __builtin_amdgcn_mfma_f32_16x16x32_bf16(Bt[n][k], At[m][k], acc[ai][bj][m][n], 0, 0, 0); __builtin_amdgcn_s_setprio(0); } while (0)
; #define PG8_WAIT_V(n) asm volatile("s_waitcnt vmcnt(" #n ")" ::: "memory")
; #define PG8_WAIT_L(n) asm volatile("s_waitcnt lgkmcnt(" #n ")" ::: "memory")
; #define PG8_BAR __builtin_amdgcn_s_barrier()
; #define PG8_SCHED __builtin_amdgcn_sched_barrier(0)
; __device__ __forceinline__ void gemm_phase(LAS unsigned char* lds, const GemmD g, const Sched& S, const Epi& E) {
;     ...
;         for (int t = 0; t < nt; t += 2) {
;             const bool last = (t == nt - 2);
;             const char* a1 = cA + (size_t)(t + 1) * kstep;
;             const char* a2 = last ? nA : cA + (size_t)(t + 2) * kstep; const char* b2 = last ? nB : cB + (size_t)(t + 2) * kstep;
;             const char* a3 = a2 + kstep; const char* b3 = b2 + kstep;
;             PG8_LDB(B0, 0, 0); PG8_LDB(B1, 0, 1); PG8_SCHED; PG8_LDA(At, 0, 0); PG8_STAGE(PG8_SA(1, 1), a1 + hstepA, voffA);
;             PG8_WAIT_V(8); PG8_WAIT_L(0); PG8_BAR; PG8_MMA(0, 0, At, B0); PG8_MMA(0, 1, At, B1); PG8_BAR; PG8_SCHED;
;             PG8_LDA(At, 0, 1); PG8_STAGE(PG8_SB(0, 0), b2, voffB); PG8_STAGE(PG8_SB(0, 1), b2 + hstepB, voffB); PG8_STAGE(PG8_SA(0, 0), a2, voffA);
;             PG8_WAIT_V(8); PG8_WAIT_L(0); PG8_BAR; PG8_MMA(1, 0, At, B0); PG8_MMA(1, 1, At, B1); PG8_BAR; PG8_SCHED;
.LBB0_215:
	s_add_i32 s92, s26, 2
	s_add_u32 s93, s8, 0x80
	s_addc_u32 s27, s9, 0
	s_add_i32 s22, 0, 0x10000
	s_cmp_eq_u32 s11, s26
	s_cselect_b32 s27, s1, s27
	s_cselect_b32 s26, s0, s93
	s_cselect_b32 vcc_hi, s17, s35
	s_cselect_b32 vcc_lo, s16, s34
	s_add_i32 s23, 0, 0x14000
	ds_read_b128 v[130:133], v240
	ds_read_b128 v[146:149], v240 offset:1024
	ds_read_b128 v[150:153], v240 offset:2048
	ds_read_b128 v[154:157], v240 offset:3072
	ds_read_b128 v[162:165], v241
	ds_read_b128 v[166:169], v241 offset:1024
	ds_read_b128 v[170:173], v241 offset:2048
	ds_read_b128 v[174:177], v241 offset:3072
	s_add_i32 m0, s31, 0xc000
	ds_read_b128 v[182:185], v161
	ds_read_b128 v[186:189], v161 offset:1024
	ds_read_b128 v[190:193], v161 offset:2048
	ds_read_b128 v[216:219], v161 offset:3072
	ds_read_b128 v[220:223], v161 offset:4096
	ds_read_b128 v[224:227], v161 offset:5120
	ds_read_b128 v[228:231], v161 offset:6144
	ds_read_b128 v[236:239], v161 offset:7168
	global_load_lds_dwordx4 v142, s[8:9]
	s_add_i32 m0, s31, 0xe000
	s_nop 0
	global_load_lds_dwordx4 v144, s[8:9]
	s_waitcnt vmcnt(8)
	s_waitcnt lgkmcnt(0)
	s_barrier
	v_mfma_f32_16x16x32_bf16 v[126:129], v[130:133], v[182:185], v[126:129]
	v_mfma_f32_16x16x32_bf16 v[122:125], v[150:153], v[182:185], v[122:125]
	v_mfma_f32_16x16x32_bf16 v[110:113], v[130:133], v[190:193], v[110:113]
	v_mfma_f32_16x16x32_bf16 v[106:109], v[150:153], v[190:193], v[106:109]
	v_mfma_f32_16x16x32_bf16 v[94:97], v[130:133], v[220:223], v[94:97]
	v_mfma_f32_16x16x32_bf16 v[90:93], v[150:153], v[220:223], v[90:93]
	v_mfma_f32_16x16x32_bf16 v[78:81], v[130:133], v[228:231], v[78:81]
	v_mfma_f32_16x16x32_bf16 v[74:77], v[150:153], v[228:231], v[74:77]
	v_mfma_f32_16x16x32_bf16 v[126:129], v[146:149], v[186:189], v[126:129]
	v_mfma_f32_16x16x32_bf16 v[122:125], v[154:157], v[186:189], v[122:125]
	v_mfma_f32_16x16x32_bf16 v[110:113], v[146:149], v[216:219], v[110:113]
	v_mfma_f32_16x16x32_bf16 v[106:109], v[154:157], v[216:219], v[106:109]
	v_mfma_f32_16x16x32_bf16 v[94:97], v[146:149], v[224:227], v[94:97]
	v_mfma_f32_16x16x32_bf16 v[90:93], v[154:157], v[224:227], v[90:93]
	v_mfma_f32_16x16x32_bf16 v[78:81], v[146:149], v[236:239], v[78:81]
	v_mfma_f32_16x16x32_bf16 v[74:77], v[154:157], v[236:239], v[74:77]
	v_mfma_f32_16x16x32_bf16 v[118:121], v[162:165], v[182:185], v[118:121]
	v_mfma_f32_16x16x32_bf16 v[114:117], v[170:173], v[182:185], v[114:117]
	v_mfma_f32_16x16x32_bf16 v[102:105], v[162:165], v[190:193], v[102:105]
	v_mfma_f32_16x16x32_bf16 v[98:101], v[170:173], v[190:193], v[98:101]
	v_mfma_f32_16x16x32_bf16 v[86:89], v[162:165], v[220:223], v[86:89]
	v_mfma_f32_16x16x32_bf16 v[82:85], v[170:173], v[220:223], v[82:85]
	v_mfma_f32_16x16x32_bf16 v[70:73], v[162:165], v[228:231], v[70:73]
	v_mfma_f32_16x16x32_bf16 v[66:69], v[170:173], v[228:231], v[66:69]
	v_mfma_f32_16x16x32_bf16 v[118:121], v[166:169], v[186:189], v[118:121]
	v_mfma_f32_16x16x32_bf16 v[114:117], v[174:177], v[186:189], v[114:117]
	v_mfma_f32_16x16x32_bf16 v[102:105], v[166:169], v[216:219], v[102:105]
	v_mfma_f32_16x16x32_bf16 v[98:101], v[174:177], v[216:219], v[98:101]
	v_mfma_f32_16x16x32_bf16 v[86:89], v[166:169], v[224:227], v[86:89]
	v_mfma_f32_16x16x32_bf16 v[82:85], v[174:177], v[224:227], v[82:85]
	v_mfma_f32_16x16x32_bf16 v[70:73], v[166:169], v[236:239], v[70:73]
	v_mfma_f32_16x16x32_bf16 v[66:69], v[174:177], v[236:239], v[66:69]
	s_barrier
	s_add_i32 s22, s22, s30
	s_mov_b32 m0, s22
	ds_read_b128 v[182:185], v161 offset:16384
	ds_read_b128 v[186:189], v161 offset:17408
	ds_read_b128 v[190:193], v161 offset:18432
	ds_read_b128 v[216:219], v161 offset:19456
	ds_read_b128 v[220:223], v161 offset:20480
	ds_read_b128 v[224:227], v161 offset:21504
	ds_read_b128 v[228:231], v161 offset:22528
	ds_read_b128 v[236:239], v161 offset:23552
	global_load_lds_dwordx4 v136, vcc
	s_add_i32 m0, s22, 0x2000
	s_add_i32 s22, s23, s30
	global_load_lds_dwordx4 v140, vcc
	s_mov_b32 m0, s22
	s_nop 0
	global_load_lds_dwordx4 v253, vcc
	s_add_i32 m0, s22, 0x2000
	s_nop 0
	global_load_lds_dwordx4 v254, vcc
	s_mov_b32 m0, s31
	s_nop 0
	global_load_lds_dwordx4 v134, s[26:27]
	s_mov_b32 m0, s14
	s_nop 0
	global_load_lds_dwordx4 v138, s[26:27]
	s_waitcnt vmcnt(8)
	s_waitcnt lgkmcnt(0)
	s_barrier
	v_mfma_f32_16x16x32_bf16 v[62:65], v[130:133], v[182:185], v[62:65]
	v_mfma_f32_16x16x32_bf16 v[58:61], v[150:153], v[182:185], v[58:61]
	v_mfma_f32_16x16x32_bf16 v[46:49], v[130:133], v[190:193], v[46:49]
	v_mfma_f32_16x16x32_bf16 v[42:45], v[150:153], v[190:193], v[42:45]
	v_mfma_f32_16x16x32_bf16 v[30:33], v[130:133], v[220:223], v[30:33]
	v_mfma_f32_16x16x32_bf16 v[26:29], v[150:153], v[220:223], v[26:29]
	v_mfma_f32_16x16x32_bf16 v[14:17], v[130:133], v[228:231], v[14:17]
	v_mfma_f32_16x16x32_bf16 v[10:13], v[150:153], v[228:231], v[10:13]
	v_mfma_f32_16x16x32_bf16 v[62:65], v[146:149], v[186:189], v[62:65]
	v_mfma_f32_16x16x32_bf16 v[58:61], v[154:157], v[186:189], v[58:61]
	v_mfma_f32_16x16x32_bf16 v[46:49], v[146:149], v[216:219], v[46:49]
	v_mfma_f32_16x16x32_bf16 v[42:45], v[154:157], v[216:219], v[42:45]
	v_mfma_f32_16x16x32_bf16 v[30:33], v[146:149], v[224:227], v[30:33]
	v_mfma_f32_16x16x32_bf16 v[26:29], v[154:157], v[224:227], v[26:29]
	v_mfma_f32_16x16x32_bf16 v[14:17], v[146:149], v[236:239], v[14:17]
	v_mfma_f32_16x16x32_bf16 v[10:13], v[154:157], v[236:239], v[10:13]
	v_mfma_f32_16x16x32_bf16 v[54:57], v[162:165], v[182:185], v[54:57]
	v_mfma_f32_16x16x32_bf16 v[50:53], v[170:173], v[182:185], v[50:53]
	v_mfma_f32_16x16x32_bf16 v[38:41], v[162:165], v[190:193], v[38:41]
	v_mfma_f32_16x16x32_bf16 v[34:37], v[170:173], v[190:193], v[34:37]
	v_mfma_f32_16x16x32_bf16 v[22:25], v[162:165], v[220:223], v[22:25]
	v_mfma_f32_16x16x32_bf16 v[18:21], v[170:173], v[220:223], v[18:21]
	v_mfma_f32_16x16x32_bf16 v[6:9], v[162:165], v[228:231], v[6:9]
	v_mfma_f32_16x16x32_bf16 v[2:5], v[170:173], v[228:231], v[2:5]
	v_mfma_f32_16x16x32_bf16 v[54:57], v[166:169], v[186:189], v[54:57]
	v_mfma_f32_16x16x32_bf16 v[50:53], v[174:177], v[186:189], v[50:53]
	v_mfma_f32_16x16x32_bf16 v[38:41], v[166:169], v[216:219], v[38:41]
	v_mfma_f32_16x16x32_bf16 v[34:37], v[174:177], v[216:219], v[34:37]
	v_mfma_f32_16x16x32_bf16 v[22:25], v[166:169], v[224:227], v[22:25]
	v_mfma_f32_16x16x32_bf16 v[18:21], v[174:177], v[224:227], v[18:21]
	v_mfma_f32_16x16x32_bf16 v[6:9], v[166:169], v[236:239], v[6:9]
	v_mfma_f32_16x16x32_bf16 v[2:5], v[174:177], v[236:239], v[2:5]
	s_barrier
; #define PG8_STAGE(bufoff, gbase, voff) do { _Pragma("unroll") for (int _i = 0; _i < 2; ++_i) \
;         __builtin_amdgcn_global_load_lds((const unsigned*)((const char*)(gbase) + (voff)[_i]), (LAS unsigned*)(lds + (bufoff) + ldsw + _i * 8192), 16, 0, 0); } while (0)
; #define PG8_LDA(dst, b, h) do { _Pragma("unroll") for (int m = 0; m < 4; ++m) _Pragma("unroll") for (int k = 0; k < 2; ++k) dst[m][k] = *(const LAS bf16x8*)(lds + PG8_SA(b, h) + aoff + m * 2048 + k * 1024); } while (0)
; #define PG8_LDB(dst, b, h) do { _Pragma("unroll") for (int n = 0; n < 2; ++n) _Pragma("unroll") for (int k = 0; k < 2; ++k) dst[n][k] = *(const LAS bf16x8*)(lds + PG8_SB(b, h) + boff + n * 2048 + k * 1024); } while (0)
; #define PG8_MMA(ai, bj, At, Bt) do { __builtin_amdgcn_s_setprio(1); _Pragma("unroll") for (int m = 0; m < 4; ++m) _Pragma("unroll") for (int n = 0; n < 2; ++n) _Pragma("unroll") for (int k = 0; k < 2; ++k) \
;         acc[ai][bj][m][n] = __builtin_amdgcn_mfma_f32_16x16x32_bf16(Bt[n][k], At[m][k], acc[ai][bj][m][n], 0, 0, 0); __builtin_amdgcn_s_setprio(0); } while (0)
; #define PG8_WAIT_V(n) asm volatile("s_waitcnt vmcnt(" #n ")" ::: "memory")
; #define PG8_WAIT_L(n) asm volatile("s_waitcnt lgkmcnt(" #n ")" ::: "memory")
; #define PG8_BAR __builtin_amdgcn_s_barrier()
; #define PG8_SCHED __builtin_amdgcn_sched_barrier(0)
; __device__ __forceinline__ void gemm_phase(LAS unsigned char* lds, const GemmD g, const Sched& S, const Epi& E) {
;     ...
;             PG8_LDB(B0, 1, 0); PG8_LDB(B1, 1, 1); PG8_SCHED; PG8_LDA(At, 1, 0); PG8_STAGE(PG8_SA(0, 1), a2 + hstepA, voffA);
;             PG8_WAIT_V(8); PG8_WAIT_L(0); PG8_BAR; PG8_MMA(0, 0, At, B0); PG8_MMA(0, 1, At, B1); PG8_BAR; PG8_SCHED;
;             PG8_LDA(At, 1, 1); PG8_STAGE(PG8_SB(1, 0), b3, voffB); PG8_STAGE(PG8_SB(1, 1), b3 + hstepB, voffB); PG8_STAGE(PG8_SA(1, 0), a3, voffA);
;             PG8_WAIT_V(8); PG8_WAIT_L(0); PG8_BAR; PG8_MMA(1, 0, At, B0); PG8_MMA(1, 1, At, B1); PG8_BAR; PG8_SCHED;
;         }
	s_add_i32 s22, 0, 0x18000
	s_add_i32 s23, 0, 0x1c000
	ds_read_b128 v[130:133], v242
	ds_read_b128 v[146:149], v242 offset:1024
	ds_read_b128 v[150:153], v242 offset:2048
	ds_read_b128 v[154:157], v242 offset:3072
	ds_read_b128 v[162:165], v243
	ds_read_b128 v[166:169], v243 offset:1024
	ds_read_b128 v[170:173], v243 offset:2048
	ds_read_b128 v[174:177], v243 offset:3072
	s_mov_b32 m0, s15
	ds_read_b128 v[182:185], v161 offset:32768
	ds_read_b128 v[186:189], v161 offset:33792
	ds_read_b128 v[190:193], v161 offset:34816
	ds_read_b128 v[216:219], v161 offset:35840
	ds_read_b128 v[220:223], v161 offset:36864
	ds_read_b128 v[224:227], v161 offset:37888
	ds_read_b128 v[228:231], v161 offset:38912
	ds_read_b128 v[236:239], v161 offset:39936
	global_load_lds_dwordx4 v142, s[26:27]
	s_mov_b32 m0, s10
	s_nop 0
	global_load_lds_dwordx4 v144, s[26:27]
	s_waitcnt vmcnt(8)
	s_waitcnt lgkmcnt(0)
	s_barrier
	v_mfma_f32_16x16x32_bf16 v[126:129], v[130:133], v[182:185], v[126:129]
	v_mfma_f32_16x16x32_bf16 v[122:125], v[150:153], v[182:185], v[122:125]
	v_mfma_f32_16x16x32_bf16 v[110:113], v[130:133], v[190:193], v[110:113]
	v_mfma_f32_16x16x32_bf16 v[106:109], v[150:153], v[190:193], v[106:109]
	v_mfma_f32_16x16x32_bf16 v[94:97], v[130:133], v[220:223], v[94:97]
	v_mfma_f32_16x16x32_bf16 v[90:93], v[150:153], v[220:223], v[90:93]
	v_mfma_f32_16x16x32_bf16 v[78:81], v[130:133], v[228:231], v[78:81]
	v_mfma_f32_16x16x32_bf16 v[74:77], v[150:153], v[228:231], v[74:77]
	v_mfma_f32_16x16x32_bf16 v[126:129], v[146:149], v[186:189], v[126:129]
	v_mfma_f32_16x16x32_bf16 v[122:125], v[154:157], v[186:189], v[122:125]
	v_mfma_f32_16x16x32_bf16 v[110:113], v[146:149], v[216:219], v[110:113]
	v_mfma_f32_16x16x32_bf16 v[106:109], v[154:157], v[216:219], v[106:109]
	v_mfma_f32_16x16x32_bf16 v[94:97], v[146:149], v[224:227], v[94:97]
	v_mfma_f32_16x16x32_bf16 v[90:93], v[154:157], v[224:227], v[90:93]
	v_mfma_f32_16x16x32_bf16 v[78:81], v[146:149], v[236:239], v[78:81]
	v_mfma_f32_16x16x32_bf16 v[74:77], v[154:157], v[236:239], v[74:77]
	v_mfma_f32_16x16x32_bf16 v[118:121], v[162:165], v[182:185], v[118:121]
	v_mfma_f32_16x16x32_bf16 v[114:117], v[170:173], v[182:185], v[114:117]
	v_mfma_f32_16x16x32_bf16 v[102:105], v[162:165], v[190:193], v[102:105]
	v_mfma_f32_16x16x32_bf16 v[98:101], v[170:173], v[190:193], v[98:101]
	v_mfma_f32_16x16x32_bf16 v[86:89], v[162:165], v[220:223], v[86:89]
	v_mfma_f32_16x16x32_bf16 v[82:85], v[170:173], v[220:223], v[82:85]
	v_mfma_f32_16x16x32_bf16 v[70:73], v[162:165], v[228:231], v[70:73]
	v_mfma_f32_16x16x32_bf16 v[66:69], v[170:173], v[228:231], v[66:69]
	v_mfma_f32_16x16x32_bf16 v[118:121], v[166:169], v[186:189], v[118:121]
	v_mfma_f32_16x16x32_bf16 v[114:117], v[174:177], v[186:189], v[114:117]
	v_mfma_f32_16x16x32_bf16 v[102:105], v[166:169], v[216:219], v[102:105]
	v_mfma_f32_16x16x32_bf16 v[98:101], v[174:177], v[216:219], v[98:101]
	v_mfma_f32_16x16x32_bf16 v[86:89], v[166:169], v[224:227], v[86:89]
	v_mfma_f32_16x16x32_bf16 v[82:85], v[174:177], v[224:227], v[82:85]
	v_mfma_f32_16x16x32_bf16 v[70:73], v[166:169], v[236:239], v[70:73]
	v_mfma_f32_16x16x32_bf16 v[66:69], v[174:177], v[236:239], v[66:69]
	s_barrier
	s_add_i32 s22, s22, s30
	s_add_u32 vcc_lo, vcc_lo, s84
	s_addc_u32 vcc_hi, vcc_hi, s85
	s_add_u32 s26, s26, s84
	s_addc_u32 s27, s27, s85
	s_mov_b32 m0, s22
	ds_read_b128 v[182:185], v161 offset:49152
	ds_read_b128 v[186:189], v161 offset:50176
	ds_read_b128 v[190:193], v161 offset:51200
	ds_read_b128 v[216:219], v161 offset:52224
	ds_read_b128 v[220:223], v161 offset:53248
	ds_read_b128 v[224:227], v161 offset:54272
	ds_read_b128 v[228:231], v161 offset:55296
	ds_read_b128 v[236:239], v161 offset:56320
	global_load_lds_dwordx4 v136, vcc
	s_add_i32 m0, s22, 0x2000
	s_add_i32 s22, s23, s30
	global_load_lds_dwordx4 v140, vcc
	s_mov_b32 m0, s22
	s_nop 0
	global_load_lds_dwordx4 v253, vcc
	s_add_i32 m0, s22, 0x2000
	s_nop 0
	global_load_lds_dwordx4 v254, vcc
	s_mov_b32 m0, s18
	s_nop 0
	global_load_lds_dwordx4 v134, s[26:27]
	s_mov_b32 m0, s19
	s_nop 0
	global_load_lds_dwordx4 v138, s[26:27]
	s_waitcnt vmcnt(8)
	s_waitcnt lgkmcnt(0)
	s_barrier
	v_mfma_f32_16x16x32_bf16 v[62:65], v[130:133], v[182:185], v[62:65]
	v_mfma_f32_16x16x32_bf16 v[58:61], v[150:153], v[182:185], v[58:61]
	v_mfma_f32_16x16x32_bf16 v[46:49], v[130:133], v[190:193], v[46:49]
	v_mfma_f32_16x16x32_bf16 v[42:45], v[150:153], v[190:193], v[42:45]
	v_mfma_f32_16x16x32_bf16 v[30:33], v[130:133], v[220:223], v[30:33]
	v_mfma_f32_16x16x32_bf16 v[26:29], v[150:153], v[220:223], v[26:29]
	v_mfma_f32_16x16x32_bf16 v[14:17], v[130:133], v[228:231], v[14:17]
	v_mfma_f32_16x16x32_bf16 v[10:13], v[150:153], v[228:231], v[10:13]
	v_mfma_f32_16x16x32_bf16 v[62:65], v[146:149], v[186:189], v[62:65]
	v_mfma_f32_16x16x32_bf16 v[58:61], v[154:157], v[186:189], v[58:61]
	v_mfma_f32_16x16x32_bf16 v[46:49], v[146:149], v[216:219], v[46:49]
	v_mfma_f32_16x16x32_bf16 v[42:45], v[154:157], v[216:219], v[42:45]
	v_mfma_f32_16x16x32_bf16 v[30:33], v[146:149], v[224:227], v[30:33]
	v_mfma_f32_16x16x32_bf16 v[26:29], v[154:157], v[224:227], v[26:29]
	v_mfma_f32_16x16x32_bf16 v[14:17], v[146:149], v[236:239], v[14:17]
	v_mfma_f32_16x16x32_bf16 v[10:13], v[154:157], v[236:239], v[10:13]
	v_mfma_f32_16x16x32_bf16 v[54:57], v[162:165], v[182:185], v[54:57]
	v_mfma_f32_16x16x32_bf16 v[50:53], v[170:173], v[182:185], v[50:53]
	v_mfma_f32_16x16x32_bf16 v[38:41], v[162:165], v[190:193], v[38:41]
	v_mfma_f32_16x16x32_bf16 v[34:37], v[170:173], v[190:193], v[34:37]
	v_mfma_f32_16x16x32_bf16 v[22:25], v[162:165], v[220:223], v[22:25]
	v_mfma_f32_16x16x32_bf16 v[18:21], v[170:173], v[220:223], v[18:21]
	v_mfma_f32_16x16x32_bf16 v[6:9], v[162:165], v[228:231], v[6:9]
	v_mfma_f32_16x16x32_bf16 v[2:5], v[170:173], v[228:231], v[2:5]
	v_mfma_f32_16x16x32_bf16 v[54:57], v[166:169], v[186:189], v[54:57]
	v_mfma_f32_16x16x32_bf16 v[50:53], v[174:177], v[186:189], v[50:53]
	v_mfma_f32_16x16x32_bf16 v[38:41], v[166:169], v[216:219], v[38:41]
	v_mfma_f32_16x16x32_bf16 v[34:37], v[174:177], v[216:219], v[34:37]
	v_mfma_f32_16x16x32_bf16 v[22:25], v[166:169], v[224:227], v[22:25]
	v_mfma_f32_16x16x32_bf16 v[18:21], v[174:177], v[224:227], v[18:21]
	v_mfma_f32_16x16x32_bf16 v[6:9], v[166:169], v[236:239], v[6:9]
	v_mfma_f32_16x16x32_bf16 v[2:5], v[174:177], v[236:239], v[2:5]
	s_barrier
	s_add_u32 s8, s8, 0x100
	s_addc_u32 s9, s9, 0
	s_add_u32 s34, s34, 0x100
	s_addc_u32 s35, s35, 0
	s_cmp_ge_u32 s92, s12
	s_mov_b32 s26, s92
	s_cbranch_scc0 .LBB0_215

; template <bool COOP>
; __global__ void __launch_bounds__(512, 2) fwd_kernel(Params p) {
;     ...
;     }
; }
.LBB0_641:
	s_nop 0
	s_nop 0
	s_nop 0
	s_nop 0
	s_nop 0
	s_nop 0
	s_nop 0
	s_nop 0
	s_nop 0
	s_nop 0
	s_nop 0
	s_nop 0
	s_nop 0
	s_nop 0
	s_nop 0
	s_nop 0
	s_nop 0
	s_nop 0
	s_nop 0
	s_nop 0
	s_nop 0
	s_nop 0
	s_nop 0
	s_nop 0
	s_nop 0
	s_nop 0
	s_nop 0
	s_nop 0
	s_nop 0
	s_nop 0
	s_nop 0
	s_nop 0
	s_nop 0
	s_nop 0
	s_nop 0
	s_nop 0
	s_nop 0
	s_nop 0
	s_nop 0
	s_nop 0
	s_nop 0
	s_nop 0
	s_nop 0
	s_nop 0
	s_nop 0
	s_nop 0
	s_nop 0
	s_nop 0
	s_nop 0
	s_nop 0
	s_nop 0
	s_nop 0
	s_nop 0
	s_nop 0
	s_nop 0
	s_nop 0
	s_nop 0
	s_nop 0
	s_nop 0
	s_nop 0
	s_nop 0
	s_nop 0
	s_nop 0
	s_nop 0
	s_nop 0
	s_nop 0
	s_nop 0
	s_nop 0
	s_nop 0
	s_nop 0
	s_nop 0
	s_nop 0
	s_nop 0
	s_nop 0
	s_nop 0
	s_nop 0
	s_nop 0
	s_nop 0
	s_nop 0
	s_nop 0
	s_nop 0
	s_nop 0
	s_nop 0
	s_nop 0
	s_nop 0
	s_nop 0
	s_nop 0
	s_nop 0
	s_nop 0
	s_nop 0
	s_nop 0
	s_nop 0
	s_nop 0
	s_nop 0
	s_nop 0
	s_nop 0
	s_nop 0
	s_nop 0
	s_nop 0
	s_nop 0
	s_nop 0
	s_nop 0
	s_nop 0
	s_nop 0
	s_nop 0
	s_nop 0
	s_nop 0
	s_nop 0
	s_nop 0
	s_nop 0
	s_nop 0
	s_nop 0
	s_nop 0
	s_nop 0
	s_nop 0
	s_nop 0
	s_nop 0
	s_nop 0
	s_nop 0
	s_nop 0
	s_nop 0
	s_nop 0
	s_nop 0
	s_nop 0
	s_nop 0
	s_nop 0
	s_nop 0
	s_nop 0
	s_nop 0
	s_nop 0
	s_nop 0
	s_nop 0
	s_nop 0
	s_nop 0
	s_nop 0
	s_nop 0
	s_nop 0
	s_nop 0
	s_nop 0
	s_nop 0
	s_nop 0
	s_nop 0
	s_nop 0
	s_nop 0
	s_nop 0
	s_nop 0
	s_nop 0
	s_nop 0
	s_nop 0
	s_nop 0
	s_nop 0
	s_nop 0
	s_nop 0
	s_nop 0
	s_nop 0
	s_nop 0
	s_nop 0
	s_nop 0
	s_nop 0
	s_nop 0
	s_nop 0
	s_nop 0
	s_nop 0
	s_nop 0
	s_nop 0
	s_nop 0
	s_nop 0
	s_nop 0
	s_nop 0
	s_nop 0
	s_nop 0
	s_nop 0
	s_nop 0
	s_nop 0
	s_nop 0
	s_nop 0
	s_nop 0
	s_nop 0
	s_nop 0
	s_nop 0
	s_nop 0
	s_nop 0
	s_nop 0
	s_nop 0
	s_nop 0
	s_nop 0
	s_nop 0
	s_nop 0
	s_nop 0
	s_nop 0
	s_nop 0
	s_nop 0
	s_nop 0
	s_nop 0
	s_nop 0
	s_nop 0
	s_nop 0
	s_nop 0
	s_nop 0
	s_nop 0
	s_nop 0
	s_nop 0
	s_nop 0
	s_nop 0
	s_nop 0
	s_nop 0
	s_nop 0
	s_nop 0
	s_nop 0
	s_nop 0
	s_nop 0
	s_nop 0
	s_nop 0
	s_nop 0
	s_nop 0
	s_nop 0
	s_nop 0
	s_nop 0
	s_nop 0
	s_nop 0
	s_nop 0
	s_nop 0
	s_nop 0
	s_nop 0
	s_nop 0
	s_nop 0
	s_nop 0
	s_nop 0
	s_nop 0
	s_nop 0
	s_nop 0
	s_nop 0
	s_nop 0
	s_nop 0
	s_nop 0
	s_nop 0
	s_nop 0
	s_nop 0
	s_nop 0
	s_nop 0
	s_nop 0
	s_endpgm
